# softmax subtraction folded into QK^T accumulator init (C = -m_ref, rewritten on the rare rescale path); staging offset registers moved to v184-193/v207-212
# speedup vs baseline: 1.0548x; 1.0060x over previous
; #define LAS __attribute__((address_space(3)))
; #define AT_LOAD(st) do { _Pragma("unroll") for (int e = 0; e < 3; ++e) pk[e] = *(const u32x4*)(kbase + (size_t)((st) * 64 + krow[e]) * 768 + kcol[e] * 8); \
;         _Pragma("unroll") for (int e = 0; e < 2; ++e) { const int c = tid + 512 * e; pv[e] = *(const u32x4*)(vbase + (size_t)(c >> 3) * SEQ + (st) * 64 + (c & 7) * 8); } } while (0)
; DI void attn_unit(const Params& p, int b, int h, int qb, LAS unsigned char* lds, int tid, int lane, int wave) {
;     unsigned char* ws = p.ws;
;     const bf16_t* Q = (const bf16_t*)(ws + WS_QR); const bf16_t* KB = (const bf16_t*)(ws + WS_K); const bf16_t* VT = (const bf16_t*)(ws + WS_VT);
;     const bf16_t* Z = (const bf16_t*)(ws + WS_Z); bf16_t* OB = (bf16_t*)(ws + WS_KVR);
;     const int g = wave >> 2, w4 = wave & 3, r = lane & 31, hh = lane >> 5;
;     const int qr0 = qb * 128 + w4 * 32, nst = 2 * (qb + 1);
;     const size_t tokb = (size_t)b * SEQ;
;     bf16x8 qf[12];
;     { const bf16_t* qp = Q + (tokb + qr0 + r) * 768 + h * 192 + 8 * hh;
; #pragma unroll
;       for (int kk = 0; kk < 12; ++kk) qf[kk] = *(const bf16x8*)(qp + 16 * kk); }
;     f32x16 o[4];
; #pragma unroll
;     for (int i = 0; i < 4; ++i)
; #pragma unroll
;         for (int j = 0; j < 16; ++j) o[i][j] = 0.f;
;     float mrow = -INFINITY, lrow = 0.f;
;     const bf16_t* kbase = KB + tokb * 768 + h * 192;
;     const bf16_t* vbase = VT + (size_t)((b * 4 + h) * 128) * SEQ;
;     int krow[3], kcol[3];
; #pragma unroll
;     for (int e = 0; e < 3; ++e) { const int c = tid + 512 * e; krow[e] = c / 24; kcol[e] = c % 24; }
;     u32x4 pk[3], pv[2];
;     ...
;     AT_LOAD(0); AT_WRITE(0);
;     __syncthreads();
.LBB0_426:
	s_mov_b32 s3, s33
	v_mbcnt_lo_u32_b32 v183, -1, 0
	v_mbcnt_hi_u32_b32 v183, -1, v183
	s_mov_b32 s5, 0x2aaaaaab
	v_lshl_add_u32 v14, s3, 6, v183
	v_mul_hi_i32 v0, v14, s5
	v_lshrrev_b32_e32 v2, 31, v0
	v_ashrrev_i32_e32 v0, 2, v0
	v_add_u32_e32 v40, v0, v2
	s_bfe_u32 s4, s73, 0x20006
	s_bfe_u32 s2, s73, 0x20004
	v_mul_lo_u32 v0, v40, 24
	s_waitcnt vmcnt(0)
	v_add_u32_e32 v20, 0x200, v14
	s_lshl_b32 s0, s2, 20
	s_lshl_b32 s1, s4, 22
	v_sub_u32_e32 v41, v14, v0
	v_mul_hi_i32 v0, v20, s5
	s_or_b32 s92, s1, s0
	s_mov_b64 s[0:1], s[50:51]
	v_lshrrev_b32_e32 v2, 31, v0
	v_ashrrev_i32_e32 v0, 2, v0
	s_and_b32 s94, s73, 15
	v_add_u32_e32 v42, v0, v2
	s_xor_b32 s0, s94, 31
	s_and_b32 s20, s3, 3
	v_mul_lo_u32 v0, v42, 24
	s_lshl_b32 s6, s0, 7
	s_lshl_b32 s0, s20, 5
	s_mul_i32 s67, s2, 0xc0
	v_sub_u32_e32 v43, v20, v0
	v_add_u32_e32 v0, 0x400, v14
	s_or_b32 s36, s0, s6
	s_lshl_b32 s66, s4, 12
	s_lshl_b32 s0, s67, 1
	s_ashr_i32 s21, s3, 2
	s_mul_i32 s7, s4, 0x600000
	v_readlane_b32 s1, v254, 52
	v_mul_hi_i32 v2, v0, s5
	s_add_u32 s1, s1, s7
	v_readlane_b32 s4, v254, 53
	v_lshrrev_b32_e32 v3, 31, v2
	v_ashrrev_i32_e32 v2, 2, v2
	s_addc_u32 s4, s4, 0
	v_add_u32_e32 v44, v2, v3
	v_mul_lo_u32 v2, v44, 24
	s_add_u32 s52, s1, s0
	v_sub_u32_e32 v45, v0, v2
	s_addc_u32 s53, s4, 0
	v_lshlrev_b32_e32 v4, 3, v41
	v_lshlrev_b32_e32 v6, 3, v43
	v_mov_b64_e32 v[10:11], s[52:53]
	v_ashrrev_i32_e32 v5, 31, v4
	v_ashrrev_i32_e32 v7, 31, v6
	v_lshlrev_b32_e32 v12, 3, v45
	v_readlane_b32 s1, v254, 50
	v_mad_i64_i32 v[2:3], s[4:5], v40, s76, v[10:11]
	v_lshlrev_b64 v[22:23], 1, v[4:5]
	v_mad_i64_i32 v[4:5], s[4:5], v42, s76, v[10:11]
	v_lshlrev_b64 v[24:25], 1, v[6:7]
	v_ashrrev_i32_e32 v13, 31, v12
	s_add_u32 s74, s1, s92
	v_readlane_b32 s1, v254, 51
	v_lshlrev_b32_e32 v0, 4, v183
	v_ashrrev_i32_e32 v28, 3, v14
	v_lshl_add_u64 v[2:3], v[2:3], 0, v[22:23]
	v_lshl_add_u64 v[6:7], v[4:5], 0, v[24:25]
	v_mad_i64_i32 v[10:11], s[4:5], v44, s76, v[10:11]
	v_lshlrev_b64 v[26:27], 1, v[12:13]
	s_addc_u32 s75, s1, 0
	v_and_b32_e32 v0, 0x70, v0
	v_ashrrev_i32_e32 v29, 31, v28
	v_ashrrev_i32_e32 v32, 3, v20
	global_load_dwordx4 v[2:5], v[2:3], off
	s_nop 0
	global_load_dwordx4 v[6:9], v[6:7], off
	v_lshl_add_u64 v[10:11], v[10:11], 0, v[26:27]
	v_lshl_add_u64 v[18:19], s[74:75], 0, v[0:1]
	v_lshlrev_b64 v[30:31], 13, v[28:29]
	v_ashrrev_i32_e32 v33, 31, v32
	global_load_dwordx4 v[10:13], v[10:11], off
	v_lshl_add_u64 v[14:15], v[18:19], 0, v[30:31]
	v_lshlrev_b64 v[34:35], 13, v[32:33]
	v_and_b32_e32 v29, 31, v183
	v_readlane_b32 s4, v254, 48
	global_load_dwordx4 v[14:17], v[14:15], off
	v_lshl_add_u64 v[18:19], v[18:19], 0, v[34:35]
	v_or_b32_e32 v36, s66, v29
	v_readlane_b32 s5, v254, 49
	global_load_dwordx4 v[18:21], v[18:19], off
	v_ashrrev_i32_e32 v33, 5, v183
	v_or_b32_e32 v202, s36, v36
	v_mov_b64_e32 v[36:37], s[4:5]
	v_mad_u64_u32 v[36:37], s[4:5], v202, s76, v[36:37]
	s_mov_b32 s1, s93
	v_lshlrev_b32_e32 v38, 3, v33
	v_lshl_add_u64 v[36:37], v[36:37], 0, s[0:1]
	v_ashrrev_i32_e32 v39, 31, v38
	v_lshl_add_u64 v[36:37], v[38:39], 1, v[36:37]
	global_load_dwordx4 v[126:129], v[36:37], off
	global_load_dwordx4 v[122:125], v[36:37], off offset:32
	global_load_dwordx4 v[118:121], v[36:37], off offset:64
	global_load_dwordx4 v[114:117], v[36:37], off offset:96
	global_load_dwordx4 v[110:113], v[36:37], off offset:128
	global_load_dwordx4 v[106:109], v[36:37], off offset:160
	global_load_dwordx4 v[102:105], v[36:37], off offset:192
	global_load_dwordx4 v[98:101], v[36:37], off offset:224
	global_load_dwordx4 v[94:97], v[36:37], off offset:256
	global_load_dwordx4 v[90:93], v[36:37], off offset:288
	global_load_dwordx4 v[86:89], v[36:37], off offset:320
	global_load_dwordx4 v[82:85], v[36:37], off offset:352
	v_mul_lo_u32 v207, v40, s77
	v_lshlrev_b32_e32 v208, 4, v41
	v_add3_u32 v36, 0, v207, v208
	v_mul_lo_u32 v209, v42, s77
	v_lshlrev_b32_e32 v210, 4, v43
	v_mul_lo_u32 v211, v44, s77
	v_lshlrev_b32_e32 v212, 4, v45
	s_movk_i32 s0, 0x90
	v_bfe_u32 v222, v0, 4, 1
	v_and_b32_e32 v213, 0x60, v0
	v_lshl_or_b32 v213, v222, 3, v213
	v_mul_lo_u32 v214, v28, s0
	v_mul_lo_u32 v215, v32, s0
	s_lshl_b32 s56, s21, 5
	v_lshlrev_b32_e32 v182, 2, v33
	v_or_b32_e32 v205, s36, v29
	s_or_b32 s57, s36, 31
	s_or_b32 s59, s6, 64
	v_or_b32_e32 v30, v30, v0
	s_mov_b64 s[0:1], 0xe600080
	v_or_b32_e32 v34, v34, v0
	s_add_u32 s54, s7, 0xce18000
	s_addc_u32 s55, 0, 0
	v_mov_b32_e32 v0, 0x180
	s_mov_b32 s62, 0
	v_mov_b32_e32 v203, 0
	v_mov_b32_e32 v204, 0xff800000
	s_mov_b32 s63, 0
	s_waitcnt vmcnt(16)
	ds_write_b128 v36, v[2:5]
	v_add3_u32 v2, 0, v209, v210
	s_waitcnt vmcnt(15)
	ds_write_b128 v2, v[6:9]
	v_add3_u32 v2, 0, v211, v212
	v_lshlrev_b32_e32 v3, 4, v33
	v_mov_b32_e32 v6, v1
	s_waitcnt vmcnt(14)
	ds_write_b128 v2, v[10:13]
	v_add3_u32 v2, v213, v214, s65
	v_mov_b32_e32 v7, v1
	v_mov_b32_e32 v8, v1
	v_mov_b32_e32 v9, v1
	s_waitcnt vmcnt(13)
	ds_write2_b64 v2, v[14:15], v[16:17] offset1:2
	v_add3_u32 v2, v213, v215, s65
	v_mov_b32_e32 v14, v1
	v_mov_b32_e32 v15, v1
	s_waitcnt vmcnt(12)
; #define AT_LOAD(st) do { _Pragma("unroll") for (int e = 0; e < 3; ++e) pk[e] = *(const u32x4*)(kbase + (size_t)((st) * 64 + krow[e]) * 768 + kcol[e] * 8); \
;         _Pragma("unroll") for (int e = 0; e < 2; ++e) { const int c = tid + 512 * e; pv[e] = *(const u32x4*)(vbase + (size_t)(c >> 3) * SEQ + (st) * 64 + (c & 7) * 8); } } while (0)
; DI void attn_unit(const Params& p, int b, int h, int qb, LAS unsigned char* lds, int tid, int lane, int wave) {
;     ...
;     f32x16 o[4];
; #pragma unroll
;     for (int i = 0; i < 4; ++i)
; #pragma unroll
;         for (int j = 0; j < 16; ++j) o[i][j] = 0.f;
;     float mrow = -INFINITY, lrow = 0.f;
;     const bf16_t* kbase = KB + tokb * 768 + h * 192;
;     const bf16_t* vbase = VT + (size_t)((b * 4 + h) * 128) * SEQ;
;     int krow[3], kcol[3];
; #pragma unroll
;     for (int e = 0; e < 3; ++e) { const int c = tid + 512 * e; krow[e] = c / 24; kcol[e] = c % 24; }
;     u32x4 pk[3], pv[2];
;     ...
;     AT_LOAD(0); AT_WRITE(0);
;     __syncthreads();
	ds_write2_b64 v2, v[18:19], v[20:21] offset1:2
	v_or_b32_e32 v2, s56, v29
	v_mul_lo_u32 v2, v2, s77
	v_add3_u32 v216, 0, v2, v3
	v_mul_u32_u24_e32 v2, 0x90, v29
	v_lshlrev_b32_e32 v3, 2, v182
	v_lshl_add_u32 v3, s56, 1, v3
	v_add3_u32 v206, 0, v2, v3
	v_sub_u32_e32 v2, v205, v182
	v_subrev_u32_e32 v217, s56, v2
	v_lshl_add_u64 v[2:3], v[30:31], 0, s[92:93]
	v_lshl_add_u64 v[184:185], v[2:3], 0, s[0:1]
	v_lshl_add_u64 v[2:3], v[34:35], 0, s[92:93]
	v_lshl_add_u64 v[186:187], v[2:3], 0, s[0:1]
	v_mov_b64_e32 v[2:3], s[54:55]
	v_mad_i64_i32 v[4:5], s[0:1], v44, s76, v[2:3]
	v_mad_u64_u32 v[4:5], s[0:1], s2, v0, v[4:5]
	v_lshl_add_u64 v[188:189], v[4:5], 0, v[26:27]
	v_mad_i64_i32 v[4:5], s[0:1], v42, s76, v[2:3]
	v_mad_i64_i32 v[2:3], s[0:1], v40, s76, v[2:3]
	v_mad_u64_u32 v[4:5], s[0:1], s2, v0, v[4:5]
	v_mad_u64_u32 v[2:3], s[0:1], s2, v0, v[2:3]
	v_lshl_add_u64 v[190:191], v[4:5], 0, v[24:25]
	v_lshl_add_u64 v[192:193], v[2:3], 0, v[22:23]
	v_mov_b32_e32 v0, v1
	v_mov_b32_e32 v2, v1
	v_mov_b32_e32 v3, v1
	v_mov_b32_e32 v4, v1
	v_mov_b32_e32 v5, v1
	v_mov_b32_e32 v10, v1
	v_mov_b32_e32 v11, v1
	v_mov_b32_e32 v12, v1
	v_mov_b32_e32 v13, v1
	v_mov_b64_e32 v[64:65], v[14:15]
	v_mov_b64_e32 v[48:49], v[14:15]
	v_mov_b64_e32 v[32:33], v[14:15]
	v_mov_b64_e32 v[62:63], v[12:13]
	v_mov_b64_e32 v[60:61], v[10:11]
	v_mov_b64_e32 v[58:59], v[8:9]
	v_mov_b64_e32 v[56:57], v[6:7]
	v_mov_b64_e32 v[54:55], v[4:5]
	v_mov_b64_e32 v[52:53], v[2:3]
	v_mov_b64_e32 v[50:51], v[0:1]
	v_mov_b64_e32 v[46:47], v[12:13]
	v_mov_b64_e32 v[44:45], v[10:11]
	v_mov_b64_e32 v[42:43], v[8:9]
	v_mov_b64_e32 v[40:41], v[6:7]
	v_mov_b64_e32 v[38:39], v[4:5]
	v_mov_b64_e32 v[36:37], v[2:3]
	v_mov_b64_e32 v[34:35], v[0:1]
	v_mov_b64_e32 v[30:31], v[12:13]
	v_mov_b64_e32 v[28:29], v[10:11]
	v_mov_b64_e32 v[26:27], v[8:9]
	v_mov_b64_e32 v[24:25], v[6:7]
	v_mov_b64_e32 v[22:23], v[4:5]
	v_mov_b64_e32 v[20:21], v[2:3]
	v_mov_b64_e32 v[18:19], v[0:1]
	v_mov_b64_e32 v[16:17], v[14:15]
	v_mov_b64_e32 v[14:15], v[12:13]
	v_mov_b64_e32 v[12:13], v[10:11]
	v_mov_b64_e32 v[10:11], v[8:9]
	v_mov_b64_e32 v[8:9], v[6:7]
	v_mov_b64_e32 v[6:7], v[4:5]
	v_mov_b64_e32 v[4:5], v[2:3]
	v_mov_b64_e32 v[2:3], v[0:1]
	s_waitcnt lgkmcnt(0)
	s_barrier
	s_waitcnt vmcnt(0)
	v_mov_b64_e32 v[230:231], 0
	v_mov_b64_e32 v[232:233], 0
	v_mov_b64_e32 v[234:235], 0
	v_mov_b64_e32 v[236:237], 0
	v_mov_b64_e32 v[238:239], 0
	v_mov_b64_e32 v[240:241], 0
	v_mov_b64_e32 v[242:243], 0
	v_mov_b64_e32 v[244:245], 0
	v_mov_b32_e32 v246, 0xff800000
	v_lshl_add_u32 v222, s3, 6, v183
	v_and_b32_e32 v222, 0xff, v222
	s_movk_i32 s0, 0x600
	s_movk_i32 s1, 0x190
	s_cmp_lg_u32 s21, 0
	s_cbranch_scc1 .Lal1_b
	v_mov_b32_e32 v223, v222
	v_mul_u32_u24_e32 v224, 0xaaab, v223
	v_lshrrev_b32_e32 v224, 20, v224
	v_mul_u32_u24_e32 v225, 24, v224
	v_sub_u32_e32 v225, v223, v225
	v_lshlrev_b32_e32 v225, 4, v225
	v_mad_u32_u24 v184, v224, s0, v225
	v_mad_u32_u24 v190, v224, s1, v225
	v_add_u32_e32 v223, 256, v222
	v_mul_u32_u24_e32 v224, 0xaaab, v223
	v_lshrrev_b32_e32 v224, 20, v224
	v_mul_u32_u24_e32 v225, 24, v224
	v_sub_u32_e32 v225, v223, v225
	v_lshlrev_b32_e32 v225, 4, v225
	v_mad_u32_u24 v185, v224, s0, v225
	v_mad_u32_u24 v191, v224, s1, v225
	v_add_u32_e32 v223, 512, v222
	v_mul_u32_u24_e32 v224, 0xaaab, v223
	v_lshrrev_b32_e32 v224, 20, v224
	v_mul_u32_u24_e32 v225, 24, v224
	v_sub_u32_e32 v225, v223, v225
	v_lshlrev_b32_e32 v225, 4, v225
	v_mad_u32_u24 v186, v224, s0, v225
	v_mad_u32_u24 v192, v224, s1, v225
	v_add_u32_e32 v223, 768, v222
	v_mul_u32_u24_e32 v224, 0xaaab, v223
	v_lshrrev_b32_e32 v224, 20, v224
	v_mul_u32_u24_e32 v225, 24, v224
	v_sub_u32_e32 v225, v223, v225
	v_lshlrev_b32_e32 v225, 4, v225
	v_mad_u32_u24 v187, v224, s0, v225
	v_mad_u32_u24 v193, v224, s1, v225
	v_add_u32_e32 v223, 1024, v222
	v_mul_u32_u24_e32 v224, 0xaaab, v223
	v_lshrrev_b32_e32 v224, 20, v224
	v_mul_u32_u24_e32 v225, 24, v224
	v_sub_u32_e32 v225, v223, v225
	v_lshlrev_b32_e32 v225, 4, v225
	v_mad_u32_u24 v188, v224, s0, v225
	v_mad_u32_u24 v207, v224, s1, v225
	v_add_u32_e32 v223, 1280, v222
	v_mul_u32_u24_e32 v224, 0xaaab, v223
	v_lshrrev_b32_e32 v224, 20, v224
	v_mul_u32_u24_e32 v225, 24, v224
	v_sub_u32_e32 v225, v223, v225
	v_lshlrev_b32_e32 v225, 4, v225
	v_mad_u32_u24 v189, v224, s0, v225
	v_mad_u32_u24 v208, v224, s1, v225
	s_branch .Lal1_done
.Lal1_b:
	v_mov_b32_e32 v223, v222
	v_lshrrev_b32_e32 v224, 3, v223
	v_and_b32_e32 v225, 7, v223
	v_lshlrev_b32_e32 v184, 13, v224
	v_lshl_or_b32 v184, v225, 4, v184
	v_mul_u32_u24_e32 v224, 0x90, v224
	v_lshrrev_b32_e32 v223, 1, v225
	v_lshl_add_u32 v224, v223, 5, v224
	v_and_b32_e32 v225, 1, v225
	v_lshl_add_u32 v224, v225, 3, v224
	v_add_u32_e32 v190, 0xc800, v224
	v_add_u32_e32 v209, 0x11000, v224
	v_add_u32_e32 v223, 256, v222
	v_lshrrev_b32_e32 v224, 3, v223
	v_and_b32_e32 v225, 7, v223
	v_lshlrev_b32_e32 v185, 13, v224
	v_lshl_or_b32 v185, v225, 4, v185
	v_mul_u32_u24_e32 v224, 0x90, v224
	v_lshrrev_b32_e32 v223, 1, v225
	v_lshl_add_u32 v224, v223, 5, v224
	v_and_b32_e32 v225, 1, v225
	v_lshl_add_u32 v224, v225, 3, v224
	v_add_u32_e32 v191, 0xc800, v224
	v_add_u32_e32 v210, 0x11000, v224
	v_add_u32_e32 v223, 512, v222
	v_lshrrev_b32_e32 v224, 3, v223
	v_and_b32_e32 v225, 7, v223
	v_lshlrev_b32_e32 v186, 13, v224
	v_lshl_or_b32 v186, v225, 4, v186
	v_mul_u32_u24_e32 v224, 0x90, v224
	v_lshrrev_b32_e32 v223, 1, v225
	v_lshl_add_u32 v224, v223, 5, v224
	v_and_b32_e32 v225, 1, v225
	v_lshl_add_u32 v224, v225, 3, v224
	v_add_u32_e32 v192, 0xc800, v224
	v_add_u32_e32 v211, 0x11000, v224
	v_add_u32_e32 v223, 768, v222
	v_lshrrev_b32_e32 v224, 3, v223
	v_and_b32_e32 v225, 7, v223
	v_lshlrev_b32_e32 v187, 13, v224
	v_lshl_or_b32 v187, v225, 4, v187
	v_mul_u32_u24_e32 v224, 0x90, v224
	v_lshrrev_b32_e32 v223, 1, v225
	v_lshl_add_u32 v224, v223, 5, v224
	v_and_b32_e32 v225, 1, v225
	v_lshl_add_u32 v224, v225, 3, v224
	v_add_u32_e32 v193, 0xc800, v224
	v_add_u32_e32 v212, 0x11000, v224

; DI unsigned pk2(float lo, float hi) { f32x2 v = {lo, hi}; return __builtin_bit_cast(unsigned, __builtin_convertvector(v, bf2_t)); }
; #define MFMA32(a, b, c) __builtin_amdgcn_mfma_f32_32x32x16_bf16((a), (b), (c), 0, 0, 0)
; DI void attn_unit(const Params& p, int b, int h, int qb, LAS unsigned char* lds, int tid, int lane, int wave) {
;     ...
;             const float muse = (mrow == -INFINITY) ? 0.f : mrow;
;             float ps = 0.f;
; #pragma unroll
;             for (int j = 0; j < 16; ++j) { s[j] = __builtin_amdgcn_exp2f(s[j] - muse); ps += s[j]; }
;             lrow += ps;
; #pragma unroll
;             for (int ks = 0; ks < 2; ++ks) {
;                 u32x4 pw; pw.x = pk2(s[8 * ks], s[8 * ks + 1]); pw.y = pk2(s[8 * ks + 2], s[8 * ks + 3]); pw.z = pk2(s[8 * ks + 4], s[8 * ks + 5]); pw.w = pk2(s[8 * ks + 6], s[8 * ks + 7]);
;                 const bf16x8 pf = __builtin_bit_cast(bf16x8, pw);
;                 __builtin_amdgcn_s_setprio(1);
; #pragma unroll
;                 for (int blk = 0; blk < 4; ++blk) o[blk] = MFMA32(vf[ks][blk], pf, o[blk]);
;                 __builtin_amdgcn_s_setprio(0);
;             }
;         }
;         if (st + 1 < nst) AT_WRITE(buf ^ 1);
.LBB0_427:
	v_exp_f32_e32 v66, v66
	v_exp_f32_e32 v67, v67
	v_exp_f32_e32 v68, v68
	v_exp_f32_e32 v69, v69
	v_add_f32_e32 v194, 0, v66
	v_exp_f32_e32 v70, v70
	v_add_f32_e32 v194, v67, v194
	v_exp_f32_e32 v71, v71
	v_add_f32_e32 v194, v68, v194
	v_exp_f32_e32 v72, v72
	v_add_f32_e32 v194, v69, v194
	v_exp_f32_e32 v73, v73
	v_add_f32_e32 v194, v70, v194
	v_exp_f32_e32 v74, v74
	v_add_f32_e32 v194, v71, v194
	v_exp_f32_e32 v75, v75
	v_add_f32_e32 v194, v72, v194
	v_exp_f32_e32 v76, v76
	v_add_f32_e32 v194, v73, v194
	v_exp_f32_e32 v77, v77
	v_add_f32_e32 v194, v74, v194
	v_exp_f32_e32 v78, v78
	v_add_f32_e32 v194, v75, v194
	v_exp_f32_e32 v79, v79
	v_add_f32_e32 v194, v76, v194
	v_exp_f32_e32 v80, v80
	v_add_f32_e32 v194, v77, v194
	v_exp_f32_e32 v0, v81
	v_add_f32_e32 v81, v78, v194
	v_add_f32_e32 v81, v79, v81
	v_add_f32_e32 v81, v80, v81
	v_add_f32_e32 v81, v0, v81
	v_cvt_pk_bf16_f32 v66, v66, v67
	v_cvt_pk_bf16_f32 v67, v68, v69
	v_cvt_pk_bf16_f32 v68, v70, v71
	v_cvt_pk_bf16_f32 v69, v72, v73
	s_setprio 1
	s_waitcnt lgkmcnt(7)
	v_mfma_f32_32x32x16_bf16 v[50:65], v[166:169], v[66:69], v[50:65]
	s_waitcnt lgkmcnt(5)
	v_mfma_f32_32x32x16_bf16 v[34:49], v[170:173], v[66:69], v[34:49]
	s_waitcnt lgkmcnt(4)
	v_mfma_f32_32x32x16_bf16 v[18:33], v[178:181], v[66:69], v[18:33]
	s_waitcnt lgkmcnt(3)
	v_mfma_f32_32x32x16_bf16 v[2:17], v[174:177], v[66:69], v[2:17]
	s_setprio 0
	v_cvt_pk_bf16_f32 v66, v74, v75
	v_cvt_pk_bf16_f32 v67, v76, v77
	v_cvt_pk_bf16_f32 v68, v78, v79
	v_cvt_pk_bf16_f32 v69, v80, v0
	s_setprio 1
	s_nop 0
	v_mfma_f32_32x32x16_bf16 v[50:65], v[150:153], v[66:69], v[50:65]
	s_waitcnt lgkmcnt(2)
	v_mfma_f32_32x32x16_bf16 v[34:49], v[162:165], v[66:69], v[34:49]
	s_waitcnt lgkmcnt(1)
	v_mfma_f32_32x32x16_bf16 v[18:33], v[158:161], v[66:69], v[18:33]
	s_waitcnt lgkmcnt(0)
	v_mfma_f32_32x32x16_bf16 v[2:17], v[154:157], v[66:69], v[2:17]
	s_setprio 0
	v_add_f32_e32 v203, v203, v81
.LBB0_428:
	s_xor_b32 s0, s78, 1
	s_cmp_lg_u32 s21, 0
	s_cbranch_scc1 .Ld1_b
	s_cmp_eq_u32 s0, 0
	s_cbranch_scc1 .Ld1_a0
	s_waitcnt vmcnt(5)
	ds_write_b128 v190, v[130:133] offset:25600
	s_waitcnt vmcnt(4)
	ds_write_b128 v191, v[134:137] offset:25600
	s_waitcnt vmcnt(3)
	ds_write_b128 v192, v[138:141] offset:25600
	s_waitcnt vmcnt(2)
	ds_write_b128 v193, v[142:145] offset:25600
	s_waitcnt vmcnt(1)
	ds_write_b128 v207, v[146:149] offset:25600
	s_waitcnt vmcnt(0)
	ds_write_b128 v208, v[250:253] offset:25600
	s_branch .Ld1_join
.Ld1_a0:
	s_waitcnt vmcnt(5)
	ds_write_b128 v190, v[130:133]
	s_waitcnt vmcnt(4)
	ds_write_b128 v191, v[134:137]
	s_waitcnt vmcnt(3)
	ds_write_b128 v192, v[138:141]
	s_waitcnt vmcnt(2)
	ds_write_b128 v193, v[142:145]
	s_waitcnt vmcnt(1)
	ds_write_b128 v207, v[146:149]
	s_waitcnt vmcnt(0)
	ds_write_b128 v208, v[250:253]
	s_branch .Ld1_join
.Ld1_b:
	s_cmp_eq_u32 s0, 0
	s_cbranch_scc1 .Ld1_b0
	s_waitcnt vmcnt(3)
	ds_write2_b64 v209, v[130:131], v[132:133] offset1:2
	s_waitcnt vmcnt(2)
	ds_write2_b64 v210, v[134:135], v[136:137] offset1:2
	s_waitcnt vmcnt(1)
	ds_write2_b64 v211, v[138:139], v[140:141] offset1:2
	s_waitcnt vmcnt(0)
	ds_write2_b64 v212, v[142:143], v[144:145] offset1:2
	s_branch .Ld1_join
.Ld1_b0:
	s_waitcnt vmcnt(3)
	ds_write2_b64 v190, v[130:131], v[132:133] offset1:2
	s_waitcnt vmcnt(2)
	ds_write2_b64 v191, v[134:135], v[136:137] offset1:2
	s_waitcnt vmcnt(1)
	ds_write2_b64 v192, v[138:139], v[140:141] offset1:2
	s_waitcnt vmcnt(0)
	ds_write2_b64 v193, v[142:143], v[144:145] offset1:2

; #define LAS __attribute__((address_space(3)))
; #define MFMA32(a, b, c) __builtin_amdgcn_mfma_f32_32x32x16_bf16((a), (b), (c), 0, 0, 0)
; #define AT_LOAD(st) do { _Pragma("unroll") for (int e = 0; e < 3; ++e) pk[e] = *(const u32x4*)(kbase + (size_t)((st) * 64 + krow[e]) * 768 + kcol[e] * 8); \
;         _Pragma("unroll") for (int e = 0; e < 2; ++e) { const int c = tid + 512 * e; pv[e] = *(const u32x4*)(vbase + (size_t)(c >> 3) * SEQ + (st) * 64 + (c & 7) * 8); } } while (0)
; DI void attn_unit(const Params& p, int b, int h, int qb, LAS unsigned char* lds, int tid, int lane, int wave) {
;     ...
;         if (st + 1 < nst) AT_LOAD(st + 1);
;         const int kb = st * 64 + g * 32;
;         if (kb <= qr0 + 31) {
;             f32x16 s;
; #pragma unroll
;             for (int j = 0; j < 16; ++j) s[j] = 0.f;
;             const LAS unsigned char* kp = lds + AT_K0 + buf * AT_KB + (g * 32 + r) * 400 + hh * 16;
;             bf16x8 kf[12];
; #pragma unroll
;             for (int kk = 0; kk < 12; ++kk) kf[kk] = *(const LAS bf16x8*)(kp + kk * 32);
;             __builtin_amdgcn_sched_barrier(0);
;             __builtin_amdgcn_s_setprio(1);
; #pragma unroll
;             for (int kk = 0; kk < 12; ++kk) s = MFMA32(kf[kk], qf[kk], s);
;             __builtin_amdgcn_s_setprio(0);
;             const LAS unsigned char* vp = lds + AT_V0 + buf * AT_VB + r * 136 + (g * 32 + 4 * hh) * 2;
;             bf16x8 vf[2][4];
; #pragma unroll
;             for (int ks = 0; ks < 2; ++ks)
; #pragma unroll
;                 for (int blk = 0; blk < 4; ++blk) {
;                     const s16x4 lo = *(const LAS s16x4*)(vp + blk * 32 * 136 + ks * 32), hi = *(const LAS s16x4*)(vp + blk * 32 * 136 + ks * 32 + 16);
;                     vf[ks][blk] = __builtin_shufflevector(lo, hi, 0, 1, 2, 3, 4, 5, 6, 7);
;                 }
;             __builtin_amdgcn_sched_barrier(0);
;             if (kb + 31 > qr0) {
;                 const int qa = qr0 + r - kb - 4 * hh;
; #pragma unroll
;                 for (int j = 0; j < 16; ++j) if ((j & 3) + 8 * (j >> 2) > qa) s[j] = -INFINITY;
.LBB0_429:
	s_cmp_lg_u32 s21, 0
	s_cbranch_scc1 .Lt1_na
	global_load_dwordx4 v[130:133], v184, s[98:99]
	global_load_dwordx4 v[134:137], v185, s[98:99]
	global_load_dwordx4 v[138:141], v186, s[98:99]
	global_load_dwordx4 v[142:145], v187, s[98:99]
	global_load_dwordx4 v[146:149], v188, s[98:99]
	global_load_dwordx4 v[250:253], v189, s[98:99]
.Lt1_na:
	s_cmp_lg_u32 s21, 1
	s_cbranch_scc1 .Lt1_nb
	global_load_dwordx4 v[130:133], v184, s[100:101]
	global_load_dwordx4 v[134:137], v185, s[100:101]
	global_load_dwordx4 v[138:141], v186, s[100:101]
	global_load_dwordx4 v[142:145], v187, s[100:101]
.Lt1_nb:
	s_and_b32 s78, s63, 1
	s_add_i32 s0, s56, s62
	s_cmp_gt_i32 s0, s57
	s_cbranch_scc1 .LBB0_428
	s_mul_i32 s1, s78, 0x6400
	v_add_u32_e32 v0, s1, v216
	ds_read_b128 v[66:69], v0
	ds_read_b128 v[150:153], v0 offset:32
	ds_read_b128 v[154:157], v0 offset:64
	ds_read_b128 v[158:161], v0 offset:96
	ds_read_b128 v[162:165], v0 offset:128
	ds_read_b128 v[166:169], v0 offset:160
	ds_read_b128 v[170:173], v0 offset:192
	ds_read_b128 v[174:177], v0 offset:224
	ds_read_b128 v[178:181], v0 offset:256
	ds_read_b128 v[194:197], v0 offset:288
	ds_read_b128 v[198:201], v0 offset:320
	ds_read_b128 v[218:221], v0 offset:352
	s_setprio 1
	s_setprio 0
	s_waitcnt lgkmcnt(11)
	v_mfma_f32_32x32x16_bf16 v[66:81], v[66:69], v[126:129], v[230:245]
	s_mul_i32 s1, s78, 0x4800
	v_add_u32_e32 v0, s1, v206
	s_waitcnt lgkmcnt(10)
	v_mfma_f32_32x32x16_bf16 v[66:81], v[150:153], v[122:125], v[66:81]
	s_waitcnt lgkmcnt(9)
	v_mfma_f32_32x32x16_bf16 v[66:81], v[154:157], v[118:121], v[66:81]
	s_waitcnt lgkmcnt(8)
	v_mfma_f32_32x32x16_bf16 v[66:81], v[158:161], v[114:117], v[66:81]
	s_waitcnt lgkmcnt(7)
	v_mfma_f32_32x32x16_bf16 v[66:81], v[162:165], v[110:113], v[66:81]
	s_waitcnt lgkmcnt(6)
	v_mfma_f32_32x32x16_bf16 v[66:81], v[166:169], v[106:109], v[66:81]
	ds_read_b128 v[166:169], v0 offset:51200
	ds_read_b128 v[150:153], v0 offset:51232
	s_waitcnt lgkmcnt(7)
	v_mfma_f32_32x32x16_bf16 v[66:81], v[170:173], v[102:105], v[66:81]
	ds_read_b128 v[170:173], v0 offset:55808
	s_waitcnt lgkmcnt(7)
	v_mfma_f32_32x32x16_bf16 v[66:81], v[174:177], v[98:101], v[66:81]
	s_waitcnt lgkmcnt(6)
	v_mfma_f32_32x32x16_bf16 v[66:81], v[178:181], v[94:97], v[66:81]
	ds_read_b128 v[178:181], v0 offset:60416
	ds_read_b128 v[174:177], v0 offset:65024
	ds_read_b128 v[162:165], v0 offset:55840
	ds_read_b128 v[158:161], v0 offset:60448
	ds_read_b128 v[154:157], v0 offset:65056
	s_waitcnt lgkmcnt(10)
	v_mfma_f32_32x32x16_bf16 v[66:81], v[194:197], v[90:93], v[66:81]
	s_waitcnt lgkmcnt(9)
	v_mfma_f32_32x32x16_bf16 v[66:81], v[198:201], v[86:89], v[66:81]
	s_waitcnt lgkmcnt(8)
	v_mfma_f32_32x32x16_bf16 v[66:81], v[218:221], v[82:85], v[66:81]
	s_add_i32 s0, s0, 31
	s_cmp_le_i32 s0, s36
	s_cbranch_scc1 .LBB0_432
	v_cmp_gt_i32_e64 s[30:31], 26, v217
	v_cmp_gt_i32_e64 s[34:35], 27, v217
	v_cmp_gt_i32_e64 s[28:29], 25, v217
	s_and_b64 s[30:31], s[34:35], s[30:31]
	v_cmp_gt_i32_e64 s[26:27], 24, v217
	s_and_b64 s[28:29], s[30:31], s[28:29]
	v_cmp_gt_i32_e64 s[24:25], 19, v217
	s_and_b64 s[26:27], s[28:29], s[26:27]
	v_cmp_gt_i32_e64 s[22:23], 18, v217
	s_and_b64 s[24:25], s[26:27], s[24:25]
	v_cmp_gt_i32_e64 s[18:19], 17, v217
	s_and_b64 s[22:23], s[24:25], s[22:23]
	v_cmp_gt_i32_e64 s[16:17], 16, v217
	s_and_b64 s[18:19], s[22:23], s[18:19]
	v_cmp_gt_i32_e64 s[14:15], 11, v217
	s_and_b64 s[16:17], s[18:19], s[16:17]
	v_cmp_gt_i32_e64 s[12:13], 10, v217
	s_and_b64 s[14:15], s[16:17], s[14:15]
	v_cmp_gt_i32_e64 s[10:11], 9, v217
	s_and_b64 s[12:13], s[14:15], s[12:13]
	v_cmp_gt_i32_e64 s[8:9], 8, v217
	s_and_b64 s[10:11], s[12:13], s[10:11]
	v_cmp_gt_i32_e64 s[6:7], 3, v217
	s_and_b64 s[8:9], s[10:11], s[8:9]
	v_cmp_gt_i32_e64 s[4:5], 2, v217
	s_and_b64 s[6:7], s[8:9], s[6:7]
	v_cmp_gt_i32_e64 s[0:1], 1, v217
	s_and_b64 s[4:5], s[6:7], s[4:5]
	v_cmp_gt_i32_e32 vcc, 0, v217
	s_and_b64 s[0:1], s[4:5], s[0:1]
	s_and_b64 vcc, s[0:1], vcc
	v_cndmask_b32_e64 v81, v81, v229, s[34:35]
	v_cndmask_b32_e64 v80, v80, v229, s[30:31]
	v_cndmask_b32_e64 v79, v79, v229, s[28:29]
	v_cndmask_b32_e64 v78, v78, v229, s[26:27]
	v_cndmask_b32_e64 v77, v77, v229, s[24:25]
	v_cndmask_b32_e64 v76, v76, v229, s[22:23]
	v_cndmask_b32_e64 v75, v75, v229, s[18:19]
	v_cndmask_b32_e64 v74, v74, v229, s[16:17]
	v_cndmask_b32_e64 v73, v73, v229, s[14:15]
	v_cndmask_b32_e64 v72, v72, v229, s[12:13]
	v_cndmask_b32_e64 v71, v71, v229, s[10:11]
	v_cndmask_b32_e64 v70, v70, v229, s[8:9]
	v_cndmask_b32_e64 v69, v69, v229, s[6:7]
	v_cndmask_b32_e64 v68, v68, v229, s[4:5]
	v_cndmask_b32_e64 v67, v67, v229, s[0:1]
	v_cndmask_b32_e32 v66, v66, v229, vcc
; DI void attn_unit(const Params& p, int b, int h, int qb, LAS unsigned char* lds, int tid, int lane, int wave) {
;     ...
;             float mx = fmaxf(fmaxf(fmaxf(s[0], s[1]), fmaxf(s[2], s[3])), fmaxf(fmaxf(s[4], s[5]), fmaxf(s[6], s[7])));
;             mx = fmaxf(mx, fmaxf(fmaxf(fmaxf(s[8], s[9]), fmaxf(s[10], s[11])), fmaxf(fmaxf(s[12], s[13]), fmaxf(s[14], s[15]))));
;             { const u32x2 sw = __builtin_amdgcn_permlane32_swap(__float_as_uint(mx), __float_as_uint(mx), false, false);
;               mx = fmaxf(__uint_as_float(sw.x), __uint_as_float(sw.y)); }
;             if (__builtin_amdgcn_ballot_w64(mx > mrow + 8.0f) != 0ull) {
;                 const float mnew = fmaxf(mrow, mx);
;                 const float alpha = (mnew == -INFINITY) ? 1.0f : __builtin_amdgcn_exp2f(mrow - mnew);
;                 mrow = mnew; lrow *= alpha;
; #pragma unroll
;                 for (int i = 0; i < 4; ++i)
; #pragma unroll
;                     for (int j = 0; j < 16; ++j) o[i][j] *= alpha;
;             }
.LBB0_432:
	s_nop 8
	v_max3_f32 v0, v66, v67, v68
	v_max3_f32 v194, v69, v70, v71
	v_max3_f32 v195, v72, v73, v74
	v_max3_f32 v196, v75, v76, v77
	v_max3_f32 v197, v78, v79, v80
	v_max3_f32 v0, v0, v194, v195
	v_max3_f32 v196, v196, v197, v81
	v_max_f32_e32 v0, v0, v196
	v_mov_b32_e32 v194, v0
	s_nop 1
	v_permlane32_swap_b32_e32 v0, v194
	v_max_f32_e32 v0, v0, v194
	v_cmp_gt_f32_e32 vcc, v0, v246
	s_cbranch_vccz .LBB0_427
	v_sub_f32_e32 v0, v0, v230
	v_max_f32_e32 v0, v0, v0
	v_max_f32_e32 v194, v204, v204
	v_max_f32_e32 v194, v194, v0
	v_sub_f32_e32 v0, v204, v194
	v_exp_f32_e32 v0, v0
	v_cmp_neq_f32_e32 vcc, s58, v194
	v_mov_b32_e32 v204, v194
	s_nop 0
	v_cndmask_b32_e32 v0, 1.0, v0, vcc
	v_pk_mul_f32 v[64:65], v[64:65], v[0:1] op_sel_hi:[1,0]
	v_pk_mul_f32 v[62:63], v[62:63], v[0:1] op_sel_hi:[1,0]
	v_pk_mul_f32 v[60:61], v[60:61], v[0:1] op_sel_hi:[1,0]
	v_pk_mul_f32 v[58:59], v[58:59], v[0:1] op_sel_hi:[1,0]
	v_pk_mul_f32 v[56:57], v[56:57], v[0:1] op_sel_hi:[1,0]
	v_pk_mul_f32 v[54:55], v[54:55], v[0:1] op_sel_hi:[1,0]
	v_pk_mul_f32 v[52:53], v[52:53], v[0:1] op_sel_hi:[1,0]
	v_pk_mul_f32 v[50:51], v[50:51], v[0:1] op_sel_hi:[1,0]
	v_pk_mul_f32 v[48:49], v[48:49], v[0:1] op_sel_hi:[1,0]
	v_pk_mul_f32 v[46:47], v[46:47], v[0:1] op_sel_hi:[1,0]
	v_pk_mul_f32 v[44:45], v[44:45], v[0:1] op_sel_hi:[1,0]
	v_pk_mul_f32 v[42:43], v[42:43], v[0:1] op_sel_hi:[1,0]
	v_pk_mul_f32 v[40:41], v[40:41], v[0:1] op_sel_hi:[1,0]
	v_pk_mul_f32 v[38:39], v[38:39], v[0:1] op_sel_hi:[1,0]
	v_pk_mul_f32 v[36:37], v[36:37], v[0:1] op_sel_hi:[1,0]
	v_pk_mul_f32 v[34:35], v[34:35], v[0:1] op_sel_hi:[1,0]
	v_pk_mul_f32 v[32:33], v[32:33], v[0:1] op_sel_hi:[1,0]
	v_pk_mul_f32 v[30:31], v[30:31], v[0:1] op_sel_hi:[1,0]
	v_pk_mul_f32 v[28:29], v[28:29], v[0:1] op_sel_hi:[1,0]
	v_pk_mul_f32 v[26:27], v[26:27], v[0:1] op_sel_hi:[1,0]
	v_pk_mul_f32 v[24:25], v[24:25], v[0:1] op_sel_hi:[1,0]
	v_pk_mul_f32 v[22:23], v[22:23], v[0:1] op_sel_hi:[1,0]
	v_pk_mul_f32 v[20:21], v[20:21], v[0:1] op_sel_hi:[1,0]
	v_pk_mul_f32 v[18:19], v[18:19], v[0:1] op_sel_hi:[1,0]
	v_pk_mul_f32 v[16:17], v[16:17], v[0:1] op_sel_hi:[1,0]
	v_pk_mul_f32 v[14:15], v[14:15], v[0:1] op_sel_hi:[1,0]
	v_pk_mul_f32 v[12:13], v[12:13], v[0:1] op_sel_hi:[1,0]
	v_pk_mul_f32 v[10:11], v[10:11], v[0:1] op_sel_hi:[1,0]
	v_pk_mul_f32 v[8:9], v[8:9], v[0:1] op_sel_hi:[1,0]
	v_pk_mul_f32 v[6:7], v[6:7], v[0:1] op_sel_hi:[1,0]
	v_pk_mul_f32 v[4:5], v[4:5], v[0:1] op_sel_hi:[1,0]
	v_pk_mul_f32 v[2:3], v[2:3], v[0:1] op_sel_hi:[1,0]
	v_mul_f32_e32 v203, v203, v0
	v_add_f32_e32 v247, v230, v194
	v_sub_f32_e32 v66, v66, v247
	v_sub_f32_e32 v67, v67, v247
	v_sub_f32_e32 v68, v68, v247
	v_sub_f32_e32 v69, v69, v247
	v_sub_f32_e32 v70, v70, v247
	v_sub_f32_e32 v71, v71, v247
	v_sub_f32_e32 v72, v72, v247
	v_sub_f32_e32 v73, v73, v247
	v_sub_f32_e32 v74, v74, v247
	v_sub_f32_e32 v75, v75, v247
	v_sub_f32_e32 v76, v76, v247
	v_sub_f32_e32 v77, v77, v247
	v_sub_f32_e32 v78, v78, v247
	v_sub_f32_e32 v79, v79, v247
	v_sub_f32_e32 v80, v80, v247
	v_sub_f32_e32 v81, v81, v247
	v_xor_b32_e32 v230, 0x80000000, v194
	v_mov_b32_e32 v231, v230
	v_mov_b32_e32 v232, v230
	v_mov_b32_e32 v233, v230
	v_mov_b32_e32 v234, v230
	v_mov_b32_e32 v235, v230
	v_mov_b32_e32 v236, v230
	v_mov_b32_e32 v237, v230
	v_mov_b32_e32 v238, v230
	v_mov_b32_e32 v239, v230
	v_mov_b32_e32 v240, v230
	v_mov_b32_e32 v241, v230
	v_mov_b32_e32 v242, v230
	v_mov_b32_e32 v243, v230
	v_mov_b32_e32 v244, v230
	v_mov_b32_e32 v245, v230
	v_mov_b32_e32 v246, 0x41000000
	s_branch .LBB0_427

; #define LAS __attribute__((address_space(3)))
; #define AT_LOAD(st) do { _Pragma("unroll") for (int e = 0; e < 3; ++e) pk[e] = *(const u32x4*)(kbase + (size_t)((st) * 64 + krow[e]) * 768 + kcol[e] * 8); \
;         _Pragma("unroll") for (int e = 0; e < 2; ++e) { const int c = tid + 512 * e; pv[e] = *(const u32x4*)(vbase + (size_t)(c >> 3) * SEQ + (st) * 64 + (c & 7) * 8); } } while (0)
; DI void attn_unit(const Params& p, int b, int h, int qb, LAS unsigned char* lds, int tid, int lane, int wave) {
;     unsigned char* ws = p.ws;
;     const bf16_t* Q = (const bf16_t*)(ws + WS_QR); const bf16_t* KB = (const bf16_t*)(ws + WS_K); const bf16_t* VT = (const bf16_t*)(ws + WS_VT);
;     const bf16_t* Z = (const bf16_t*)(ws + WS_Z); bf16_t* OB = (bf16_t*)(ws + WS_KVR);
;     const int g = wave >> 2, w4 = wave & 3, r = lane & 31, hh = lane >> 5;
;     const int qr0 = qb * 128 + w4 * 32, nst = 2 * (qb + 1);
;     const size_t tokb = (size_t)b * SEQ;
;     bf16x8 qf[12];
;     { const bf16_t* qp = Q + (tokb + qr0 + r) * 768 + h * 192 + 8 * hh;
; #pragma unroll
;       for (int kk = 0; kk < 12; ++kk) qf[kk] = *(const bf16x8*)(qp + 16 * kk); }
;     f32x16 o[4];
; #pragma unroll
;     for (int i = 0; i < 4; ++i)
; #pragma unroll
;         for (int j = 0; j < 16; ++j) o[i][j] = 0.f;
;     float mrow = -INFINITY, lrow = 0.f;
;     const bf16_t* kbase = KB + tokb * 768 + h * 192;
;     const bf16_t* vbase = VT + (size_t)((b * 4 + h) * 128) * SEQ;
;     int krow[3], kcol[3];
; #pragma unroll
;     for (int e = 0; e < 3; ++e) { const int c = tid + 512 * e; krow[e] = c / 24; kcol[e] = c % 24; }
;     u32x4 pk[3], pv[2];
;     ...
;     AT_LOAD(0); AT_WRITE(0);
;     __syncthreads();
.LBB0_444:
	s_mov_b32 s3, s33
	s_mov_b64 s[0:1], s[50:51]
	s_barrier
	v_mbcnt_lo_u32_b32 v183, -1, 0
	v_mbcnt_hi_u32_b32 v183, -1, v183
	s_mov_b32 s0, 0x2aaaaaab
	v_lshl_add_u32 v14, s3, 6, v183
	v_mul_hi_i32 v0, v14, s0
	v_lshrrev_b32_e32 v2, 31, v0
	v_ashrrev_i32_e32 v0, 2, v0
	v_add_u32_e32 v40, v0, v2
	v_mul_lo_u32 v0, v40, 24
	v_add_u32_e32 v20, 0x200, v14
	v_sub_u32_e32 v41, v14, v0
	v_mul_hi_i32 v0, v20, s0
	v_lshrrev_b32_e32 v2, 31, v0
	v_ashrrev_i32_e32 v0, 2, v0
	v_add_u32_e32 v42, v0, v2
	v_mul_lo_u32 v0, v42, 24
	v_sub_u32_e32 v43, v20, v0
	v_add_u32_e32 v0, 0x400, v14
	v_mul_hi_i32 v2, v0, s0
	v_lshrrev_b32_e32 v3, 31, v2
	v_ashrrev_i32_e32 v2, 2, v2
	v_add_u32_e32 v44, v2, v3
	v_mul_lo_u32 v2, v44, 24
	v_sub_u32_e32 v45, v0, v2
	v_lshlrev_b32_e32 v4, 3, v41
	v_lshlrev_b32_e32 v6, 3, v43
	v_mov_b64_e32 v[10:11], s[52:53]
	v_ashrrev_i32_e32 v5, 31, v4
	v_ashrrev_i32_e32 v7, 31, v6
	v_lshlrev_b32_e32 v12, 3, v45
	v_mad_i64_i32 v[2:3], s[0:1], v40, s76, v[10:11]
	v_lshlrev_b64 v[22:23], 1, v[4:5]
	v_mad_i64_i32 v[4:5], s[0:1], v42, s76, v[10:11]
	v_lshlrev_b64 v[24:25], 1, v[6:7]
	v_ashrrev_i32_e32 v13, 31, v12
	v_lshlrev_b32_e32 v0, 4, v183
	v_ashrrev_i32_e32 v28, 3, v14
	v_lshl_add_u64 v[2:3], v[2:3], 0, v[22:23]
	v_lshl_add_u64 v[6:7], v[4:5], 0, v[24:25]
	v_mad_i64_i32 v[10:11], s[0:1], v44, s76, v[10:11]
	v_lshlrev_b64 v[26:27], 1, v[12:13]
	v_and_b32_e32 v0, 0x70, v0
	v_ashrrev_i32_e32 v29, 31, v28
	v_ashrrev_i32_e32 v32, 3, v20
	global_load_dwordx4 v[2:5], v[2:3], off
	s_nop 0
	global_load_dwordx4 v[6:9], v[6:7], off
	v_lshl_add_u64 v[10:11], v[10:11], 0, v[26:27]
	v_lshl_add_u64 v[18:19], s[74:75], 0, v[0:1]
	v_lshlrev_b64 v[30:31], 13, v[28:29]
	v_ashrrev_i32_e32 v33, 31, v32
	s_and_b32 s0, s72, 15
	s_and_b32 s20, s3, 3
	global_load_dwordx4 v[10:13], v[10:11], off
	v_lshl_add_u64 v[14:15], v[18:19], 0, v[30:31]
	v_lshlrev_b64 v[34:35], 13, v[32:33]
	s_lshl_b32 s4, s0, 7
	s_lshl_b32 s0, s94, 7
	s_lshl_b32 s5, s20, 5
	global_load_dwordx4 v[14:17], v[14:15], off
	v_lshl_add_u64 v[18:19], v[18:19], 0, v[34:35]
	v_and_b32_e32 v205, 31, v183
	s_or_b32 s36, s5, s0
	v_readlane_b32 s0, v254, 48
	global_load_dwordx4 v[18:21], v[18:19], off
	v_or_b32_e32 v33, s66, v205
	v_readlane_b32 s1, v254, 49
	v_or_b32_e32 v202, s36, v33
	v_ashrrev_i32_e32 v29, 5, v183
	v_mov_b64_e32 v[36:37], s[0:1]
	v_mad_u64_u32 v[36:37], s[0:1], v202, s76, v[36:37]
	s_lshl_b32 s0, s67, 1
	s_mov_b32 s1, s93
	v_lshlrev_b32_e32 v38, 3, v29
	v_lshl_add_u64 v[36:37], v[36:37], 0, s[0:1]
	v_ashrrev_i32_e32 v39, 31, v38
	v_lshl_add_u64 v[36:37], v[38:39], 1, v[36:37]
	global_load_dwordx4 v[126:129], v[36:37], off
	global_load_dwordx4 v[122:125], v[36:37], off offset:32
	global_load_dwordx4 v[118:121], v[36:37], off offset:64
	global_load_dwordx4 v[114:117], v[36:37], off offset:96
	global_load_dwordx4 v[110:113], v[36:37], off offset:128
	global_load_dwordx4 v[106:109], v[36:37], off offset:160
	global_load_dwordx4 v[102:105], v[36:37], off offset:192
	global_load_dwordx4 v[98:101], v[36:37], off offset:224
	global_load_dwordx4 v[94:97], v[36:37], off offset:256
	global_load_dwordx4 v[90:93], v[36:37], off offset:288
	global_load_dwordx4 v[86:89], v[36:37], off offset:320
	global_load_dwordx4 v[82:85], v[36:37], off offset:352
	v_mul_lo_u32 v207, v40, s77
	v_lshlrev_b32_e32 v208, 4, v41
	v_add3_u32 v33, 0, v207, v208
	v_mul_lo_u32 v209, v42, s77
	v_lshlrev_b32_e32 v210, 4, v43
	v_mul_lo_u32 v211, v44, s77
	v_lshlrev_b32_e32 v212, 4, v45
	s_movk_i32 s0, 0x90
	v_bfe_u32 v222, v0, 4, 1
	v_and_b32_e32 v213, 0x60, v0
	v_lshl_or_b32 v213, v222, 3, v213
	v_mul_lo_u32 v214, v28, s0
	s_ashr_i32 s21, s3, 2
	v_mul_lo_u32 v215, v32, s0
	s_lshl_b32 s53, s21, 5
	v_lshlrev_b32_e32 v182, 2, v29
	s_or_b32 s0, s4, s5
	v_or_b32_e32 v30, v30, v0
	v_or_b32_e32 v34, v34, v0
	s_or_b32 s52, s4, 64
	s_or_b32 s56, s36, 31
	v_mov_b32_e32 v0, v1
	v_mov_b32_e32 v203, 0
	v_mov_b32_e32 v204, 0xff800000
	s_waitcnt vmcnt(16)
	ds_write_b128 v33, v[2:5]
	v_add3_u32 v2, 0, v209, v210
	s_waitcnt vmcnt(15)
	ds_write_b128 v2, v[6:9]
	v_add3_u32 v2, 0, v211, v212
	v_lshlrev_b32_e32 v3, 4, v29
	v_mov_b32_e32 v6, v1
	v_mov_b32_e32 v7, v1
	v_mov_b32_e32 v8, v1
	s_waitcnt vmcnt(14)
	ds_write_b128 v2, v[10:13]
	v_add3_u32 v2, v213, v214, s65
	v_mov_b32_e32 v9, v1
	v_mov_b32_e32 v10, v1
	v_mov_b32_e32 v11, v1
	v_mov_b32_e32 v12, v1
	s_waitcnt vmcnt(13)
	ds_write2_b64 v2, v[14:15], v[16:17] offset1:2
	v_add3_u32 v2, v213, v215, s65
	v_mov_b32_e32 v14, v1
	v_mov_b32_e32 v15, v1
	v_mov_b32_e32 v13, v1
	s_waitcnt vmcnt(12)
	ds_write2_b64 v2, v[18:19], v[20:21] offset1:2
	v_or_b32_e32 v2, s53, v205
	v_mul_lo_u32 v2, v2, s77
	v_add3_u32 v216, 0, v2, v3
	v_mul_u32_u24_e32 v2, 0x90, v205
	v_lshlrev_b32_e32 v3, 2, v182
	v_lshl_add_u32 v3, s53, 1, v3
	v_add3_u32 v206, 0, v2, v3
	v_or_b32_e32 v2, s0, v205
	v_sub_u32_e32 v2, v2, v182
	v_subrev_u32_e32 v217, s53, v2
	v_lshl_add_u64 v[2:3], v[30:31], 0, s[92:93]
	s_mov_b64 s[0:1], 0xe600080
	v_lshl_add_u64 v[184:185], v[2:3], 0, s[0:1]
	v_lshl_add_u64 v[2:3], v[34:35], 0, s[92:93]
	v_lshl_add_u64 v[186:187], v[2:3], 0, s[0:1]
	s_mul_i32 s0, s2, 0x180
	s_add_u32 s0, s0, s54
	s_addc_u32 s1, 0, s55
	v_mov_b64_e32 v[2:3], s[0:1]
	v_mad_i64_i32 v[4:5], s[0:1], v44, s76, v[2:3]
	v_lshl_add_u64 v[188:189], v[4:5], 0, v[26:27]
	v_mad_i64_i32 v[4:5], s[0:1], v42, s76, v[2:3]
	v_mad_i64_i32 v[2:3], s[0:1], v40, s76, v[2:3]
	v_lshl_add_u64 v[190:191], v[4:5], 0, v[24:25]
	v_lshl_add_u64 v[192:193], v[2:3], 0, v[22:23]
	v_mov_b32_e32 v2, v1
	v_mov_b32_e32 v3, v1
	v_mov_b32_e32 v4, v1
	v_mov_b32_e32 v5, v1
	v_mov_b64_e32 v[64:65], v[14:15]
	v_mov_b64_e32 v[48:49], v[14:15]
	v_mov_b64_e32 v[32:33], v[14:15]
	v_mov_b64_e32 v[62:63], v[12:13]
	v_mov_b64_e32 v[60:61], v[10:11]
	v_mov_b64_e32 v[58:59], v[8:9]
	v_mov_b64_e32 v[56:57], v[6:7]
	v_mov_b64_e32 v[54:55], v[4:5]
	v_mov_b64_e32 v[52:53], v[2:3]
	v_mov_b64_e32 v[50:51], v[0:1]
	v_mov_b64_e32 v[46:47], v[12:13]
	v_mov_b64_e32 v[44:45], v[10:11]
	v_mov_b64_e32 v[42:43], v[8:9]
	v_mov_b64_e32 v[40:41], v[6:7]
	v_mov_b64_e32 v[38:39], v[4:5]
	v_mov_b64_e32 v[36:37], v[2:3]
	v_mov_b64_e32 v[34:35], v[0:1]
	v_mov_b64_e32 v[30:31], v[12:13]
	v_mov_b64_e32 v[28:29], v[10:11]
	v_mov_b64_e32 v[26:27], v[8:9]
	v_mov_b64_e32 v[24:25], v[6:7]
	v_mov_b64_e32 v[22:23], v[4:5]
	v_mov_b64_e32 v[20:21], v[2:3]
	v_mov_b64_e32 v[18:19], v[0:1]
	v_mov_b64_e32 v[16:17], v[14:15]
	s_mov_b32 s54, 0
	v_mov_b64_e32 v[14:15], v[12:13]
	v_mov_b64_e32 v[12:13], v[10:11]
	v_mov_b64_e32 v[10:11], v[8:9]
	v_mov_b64_e32 v[8:9], v[6:7]
	v_mov_b64_e32 v[6:7], v[4:5]
	v_mov_b64_e32 v[4:5], v[2:3]
	v_mov_b64_e32 v[2:3], v[0:1]
	s_mov_b32 s55, 0
	s_waitcnt lgkmcnt(0)
	s_barrier
; #define AT_LOAD(st) do { _Pragma("unroll") for (int e = 0; e < 3; ++e) pk[e] = *(const u32x4*)(kbase + (size_t)((st) * 64 + krow[e]) * 768 + kcol[e] * 8); \
;         _Pragma("unroll") for (int e = 0; e < 2; ++e) { const int c = tid + 512 * e; pv[e] = *(const u32x4*)(vbase + (size_t)(c >> 3) * SEQ + (st) * 64 + (c & 7) * 8); } } while (0)
; DI void attn_unit(const Params& p, int b, int h, int qb, LAS unsigned char* lds, int tid, int lane, int wave) {
;     ...
;     float mrow = -INFINITY, lrow = 0.f;
;     const bf16_t* kbase = KB + tokb * 768 + h * 192;
;     const bf16_t* vbase = VT + (size_t)((b * 4 + h) * 128) * SEQ;
;     int krow[3], kcol[3];
; #pragma unroll
;     for (int e = 0; e < 3; ++e) { const int c = tid + 512 * e; krow[e] = c / 24; kcol[e] = c % 24; }
;     u32x4 pk[3], pv[2];
;     ...
;     AT_LOAD(0); AT_WRITE(0);
;     __syncthreads();
	s_waitcnt vmcnt(0)
	v_mov_b64_e32 v[230:231], 0
	v_mov_b64_e32 v[232:233], 0
	v_mov_b64_e32 v[234:235], 0
	v_mov_b64_e32 v[236:237], 0
	v_mov_b64_e32 v[238:239], 0
	v_mov_b64_e32 v[240:241], 0
	v_mov_b64_e32 v[242:243], 0
	v_mov_b64_e32 v[244:245], 0
	v_mov_b32_e32 v246, 0xff800000
	v_lshl_add_u32 v222, s3, 6, v183
	v_and_b32_e32 v222, 0xff, v222
	s_movk_i32 s0, 0x600
	s_movk_i32 s1, 0x190
	s_cmp_lg_u32 s21, 0
	s_cbranch_scc1 .Lal2_b
	v_mov_b32_e32 v223, v222
	v_mul_u32_u24_e32 v224, 0xaaab, v223
	v_lshrrev_b32_e32 v224, 20, v224
	v_mul_u32_u24_e32 v225, 24, v224
	v_sub_u32_e32 v225, v223, v225
	v_lshlrev_b32_e32 v225, 4, v225
	v_mad_u32_u24 v184, v224, s0, v225
	v_mad_u32_u24 v190, v224, s1, v225
	v_add_u32_e32 v223, 256, v222
	v_mul_u32_u24_e32 v224, 0xaaab, v223
	v_lshrrev_b32_e32 v224, 20, v224
	v_mul_u32_u24_e32 v225, 24, v224
	v_sub_u32_e32 v225, v223, v225
	v_lshlrev_b32_e32 v225, 4, v225
	v_mad_u32_u24 v185, v224, s0, v225
	v_mad_u32_u24 v191, v224, s1, v225
	v_add_u32_e32 v223, 512, v222
	v_mul_u32_u24_e32 v224, 0xaaab, v223
	v_lshrrev_b32_e32 v224, 20, v224
	v_mul_u32_u24_e32 v225, 24, v224
	v_sub_u32_e32 v225, v223, v225
	v_lshlrev_b32_e32 v225, 4, v225
	v_mad_u32_u24 v186, v224, s0, v225
	v_mad_u32_u24 v192, v224, s1, v225
	v_add_u32_e32 v223, 768, v222
	v_mul_u32_u24_e32 v224, 0xaaab, v223
	v_lshrrev_b32_e32 v224, 20, v224
	v_mul_u32_u24_e32 v225, 24, v224
	v_sub_u32_e32 v225, v223, v225
	v_lshlrev_b32_e32 v225, 4, v225
	v_mad_u32_u24 v187, v224, s0, v225
	v_mad_u32_u24 v193, v224, s1, v225
	v_add_u32_e32 v223, 1024, v222
	v_mul_u32_u24_e32 v224, 0xaaab, v223
	v_lshrrev_b32_e32 v224, 20, v224
	v_mul_u32_u24_e32 v225, 24, v224
	v_sub_u32_e32 v225, v223, v225
	v_lshlrev_b32_e32 v225, 4, v225
	v_mad_u32_u24 v188, v224, s0, v225
	v_mad_u32_u24 v207, v224, s1, v225
	v_add_u32_e32 v223, 1280, v222
	v_mul_u32_u24_e32 v224, 0xaaab, v223
	v_lshrrev_b32_e32 v224, 20, v224
	v_mul_u32_u24_e32 v225, 24, v224
	v_sub_u32_e32 v225, v223, v225
	v_lshlrev_b32_e32 v225, 4, v225
	v_mad_u32_u24 v189, v224, s0, v225
	v_mad_u32_u24 v208, v224, s1, v225
	s_branch .Lal2_done

.LBB0_446:
	s_xor_b32 s0, s57, 1
	s_cmp_lg_u32 s21, 0
	s_cbranch_scc1 .Ld2_b
	s_cmp_eq_u32 s0, 0
	s_cbranch_scc1 .Ld2_a0
	s_waitcnt vmcnt(5)
	ds_write_b128 v190, v[130:133] offset:25600
	s_waitcnt vmcnt(4)
	ds_write_b128 v191, v[134:137] offset:25600
	s_waitcnt vmcnt(3)
	ds_write_b128 v192, v[138:141] offset:25600
	s_waitcnt vmcnt(2)
	ds_write_b128 v193, v[142:145] offset:25600
	s_waitcnt vmcnt(1)
	ds_write_b128 v207, v[146:149] offset:25600
	s_waitcnt vmcnt(0)
	ds_write_b128 v208, v[250:253] offset:25600
	s_branch .Ld2_join

; #define LAS __attribute__((address_space(3)))
; #define MFMA32(a, b, c) __builtin_amdgcn_mfma_f32_32x32x16_bf16((a), (b), (c), 0, 0, 0)
; DI void attn_unit(const Params& p, int b, int h, int qb, LAS unsigned char* lds, int tid, int lane, int wave) {
;     ...
;         const int kb = st * 64 + g * 32;
;         if (kb <= qr0 + 31) {
;             f32x16 s;
; #pragma unroll
;             for (int j = 0; j < 16; ++j) s[j] = 0.f;
;             const LAS unsigned char* kp = lds + AT_K0 + buf * AT_KB + (g * 32 + r) * 400 + hh * 16;
;             bf16x8 kf[12];
; #pragma unroll
;             for (int kk = 0; kk < 12; ++kk) kf[kk] = *(const LAS bf16x8*)(kp + kk * 32);
;             __builtin_amdgcn_sched_barrier(0);
;             __builtin_amdgcn_s_setprio(1);
; #pragma unroll
;             for (int kk = 0; kk < 12; ++kk) s = MFMA32(kf[kk], qf[kk], s);
;             __builtin_amdgcn_s_setprio(0);
;             const LAS unsigned char* vp = lds + AT_V0 + buf * AT_VB + r * 136 + (g * 32 + 4 * hh) * 2;
;             bf16x8 vf[2][4];
; #pragma unroll
;             for (int ks = 0; ks < 2; ++ks)
; #pragma unroll
;                 for (int blk = 0; blk < 4; ++blk) {
;                     const s16x4 lo = *(const LAS s16x4*)(vp + blk * 32 * 136 + ks * 32), hi = *(const LAS s16x4*)(vp + blk * 32 * 136 + ks * 32 + 16);
;                     vf[ks][blk] = __builtin_shufflevector(lo, hi, 0, 1, 2, 3, 4, 5, 6, 7);
;                 }
;             __builtin_amdgcn_sched_barrier(0);
;             if (kb + 31 > qr0) {
;                 const int qa = qr0 + r - kb - 4 * hh;
; #pragma unroll
;                 for (int j = 0; j < 16; ++j) if ((j & 3) + 8 * (j >> 2) > qa) s[j] = -INFINITY;
;             }
.Lt2_nb:
	s_and_b32 s57, s55, 1
	s_add_i32 s0, s53, s54
	s_cmp_gt_i32 s0, s56
	s_cbranch_scc1 .LBB0_446
	s_mul_i32 s1, s57, 0x6400
	v_add_u32_e32 v0, s1, v216
	ds_read_b128 v[66:69], v0
	ds_read_b128 v[150:153], v0 offset:32
	ds_read_b128 v[154:157], v0 offset:64
	ds_read_b128 v[158:161], v0 offset:96
	ds_read_b128 v[162:165], v0 offset:128
	ds_read_b128 v[166:169], v0 offset:160
	ds_read_b128 v[170:173], v0 offset:192
	ds_read_b128 v[174:177], v0 offset:224
	ds_read_b128 v[178:181], v0 offset:256
	ds_read_b128 v[194:197], v0 offset:288
	ds_read_b128 v[198:201], v0 offset:320
	ds_read_b128 v[218:221], v0 offset:352
	s_setprio 1
	s_setprio 0
	s_waitcnt lgkmcnt(11)
	v_mfma_f32_32x32x16_bf16 v[66:81], v[66:69], v[126:129], v[230:245]
	s_mul_i32 s1, s57, 0x4800
	v_add_u32_e32 v0, s1, v206
	s_waitcnt lgkmcnt(10)
	v_mfma_f32_32x32x16_bf16 v[66:81], v[150:153], v[122:125], v[66:81]
	s_waitcnt lgkmcnt(9)
	v_mfma_f32_32x32x16_bf16 v[66:81], v[154:157], v[118:121], v[66:81]
	s_waitcnt lgkmcnt(8)
	v_mfma_f32_32x32x16_bf16 v[66:81], v[158:161], v[114:117], v[66:81]
	s_waitcnt lgkmcnt(7)
	v_mfma_f32_32x32x16_bf16 v[66:81], v[162:165], v[110:113], v[66:81]
	s_waitcnt lgkmcnt(6)
	v_mfma_f32_32x32x16_bf16 v[66:81], v[166:169], v[106:109], v[66:81]
	ds_read_b128 v[166:169], v0 offset:51200
	ds_read_b128 v[150:153], v0 offset:51232
	s_waitcnt lgkmcnt(7)
	v_mfma_f32_32x32x16_bf16 v[66:81], v[170:173], v[102:105], v[66:81]
	ds_read_b128 v[170:173], v0 offset:55808
	s_waitcnt lgkmcnt(7)
	v_mfma_f32_32x32x16_bf16 v[66:81], v[174:177], v[98:101], v[66:81]
	s_waitcnt lgkmcnt(6)
	v_mfma_f32_32x32x16_bf16 v[66:81], v[178:181], v[94:97], v[66:81]
	ds_read_b128 v[178:181], v0 offset:60416
	ds_read_b128 v[174:177], v0 offset:65024
	ds_read_b128 v[162:165], v0 offset:55840
	ds_read_b128 v[158:161], v0 offset:60448
	ds_read_b128 v[154:157], v0 offset:65056
	s_waitcnt lgkmcnt(10)
	v_mfma_f32_32x32x16_bf16 v[66:81], v[194:197], v[90:93], v[66:81]
	s_waitcnt lgkmcnt(9)
	v_mfma_f32_32x32x16_bf16 v[66:81], v[198:201], v[86:89], v[66:81]
	s_waitcnt lgkmcnt(8)
	v_mfma_f32_32x32x16_bf16 v[66:81], v[218:221], v[82:85], v[66:81]
	s_add_i32 s0, s0, 31
	s_cmp_le_i32 s0, s36
	s_cbranch_scc1 .LBB0_450
	v_cmp_gt_i32_e64 s[30:31], 26, v217
	v_cmp_gt_i32_e64 s[34:35], 27, v217
	v_cmp_gt_i32_e64 s[28:29], 25, v217
	s_and_b64 s[30:31], s[34:35], s[30:31]
	v_cmp_gt_i32_e64 s[26:27], 24, v217
	s_and_b64 s[28:29], s[30:31], s[28:29]
	v_cmp_gt_i32_e64 s[24:25], 19, v217
	s_and_b64 s[26:27], s[28:29], s[26:27]
	v_cmp_gt_i32_e64 s[22:23], 18, v217
	s_and_b64 s[24:25], s[26:27], s[24:25]
	v_cmp_gt_i32_e64 s[18:19], 17, v217
	s_and_b64 s[22:23], s[24:25], s[22:23]
	v_cmp_gt_i32_e64 s[16:17], 16, v217
	s_and_b64 s[18:19], s[22:23], s[18:19]
	v_cmp_gt_i32_e64 s[14:15], 11, v217
	s_and_b64 s[16:17], s[18:19], s[16:17]
	v_cmp_gt_i32_e64 s[12:13], 10, v217
	s_and_b64 s[14:15], s[16:17], s[14:15]
	v_cmp_gt_i32_e64 s[10:11], 9, v217
	s_and_b64 s[12:13], s[14:15], s[12:13]
	v_cmp_gt_i32_e64 s[8:9], 8, v217
	s_and_b64 s[10:11], s[12:13], s[10:11]
	v_cmp_gt_i32_e64 s[6:7], 3, v217
	s_and_b64 s[8:9], s[10:11], s[8:9]
	v_cmp_gt_i32_e64 s[4:5], 2, v217
	s_and_b64 s[6:7], s[8:9], s[6:7]
	v_cmp_gt_i32_e64 s[0:1], 1, v217
	s_and_b64 s[4:5], s[6:7], s[4:5]
	v_cmp_gt_i32_e32 vcc, 0, v217
	s_and_b64 s[0:1], s[4:5], s[0:1]
	s_and_b64 vcc, s[0:1], vcc
	v_cndmask_b32_e64 v81, v81, v229, s[34:35]
	v_cndmask_b32_e64 v80, v80, v229, s[30:31]
	v_cndmask_b32_e64 v79, v79, v229, s[28:29]
	v_cndmask_b32_e64 v78, v78, v229, s[26:27]
	v_cndmask_b32_e64 v77, v77, v229, s[24:25]
	v_cndmask_b32_e64 v76, v76, v229, s[22:23]
	v_cndmask_b32_e64 v75, v75, v229, s[18:19]
	v_cndmask_b32_e64 v74, v74, v229, s[16:17]
	v_cndmask_b32_e64 v73, v73, v229, s[14:15]
	v_cndmask_b32_e64 v72, v72, v229, s[12:13]
	v_cndmask_b32_e64 v71, v71, v229, s[10:11]
	v_cndmask_b32_e64 v70, v70, v229, s[8:9]
	v_cndmask_b32_e64 v69, v69, v229, s[6:7]
	v_cndmask_b32_e64 v68, v68, v229, s[4:5]
	v_cndmask_b32_e64 v67, v67, v229, s[0:1]
	v_cndmask_b32_e32 v66, v66, v229, vcc
